# rmsnorm row loops (P0, P7, final): norm-weight quads loaded once before the loop instead of 3-4 in-loop reloads each behind a vmcnt(0) wait that also waited on the stores
# speedup vs baseline: 1.0119x; 1.0119x over previous
; __device__ __forceinline__ unsigned cvt_pk_bf16(float lo, float hi) { f32x2_t v = {lo, hi}; bf2_t r = __builtin_convertvector(v, bf2_t); return __builtin_bit_cast(unsigned, r); }
;     __device__ __forceinline__ bf16_t* bfp(size_t off) const { return (bf16_t*)(ws + off); }
; __device__ __forceinline__ void rms_row2_bf16(const float* xrow, size_t stride, const float* g, bf16_t* orow, int lane) {
;     const f32x4* xr0 = (const f32x4*)xrow + lane; const f32x4* xr1 = (const f32x4*)(xrow + stride) + lane; const f32x4* gr = (const f32x4*)g + lane;
;     f32x4 v0[4], v1[4]; float s0 = 0.f, s1 = 0.f;
; #pragma unroll
;     for (int j = 0; j < 4; ++j) { v0[j] = xr0[64 * j]; v1[j] = xr1[64 * j]; }
; #pragma unroll
;     for (int j = 0; j < 4; ++j) { s0 += (v0[j].x * v0[j].x + v0[j].y * v0[j].y) + (v0[j].z * v0[j].z + v0[j].w * v0[j].w); s1 += (v1[j].x * v1[j].x + v1[j].y * v1[j].y) + (v1[j].z * v1[j].z + v1[j].w * v1[j].w); }
;     const float r0 = rsqrtf(wave_sum(s0) * (1.f / 1024.f) + 1e-6f), r1 = rsqrtf(wave_sum(s1) * (1.f / 1024.f) + 1e-6f);
;     u32x2* o0 = (u32x2*)orow + lane; u32x2* o1 = (u32x2*)(orow + stride) + lane;
; #pragma unroll
;     for (int j = 0; j < 4; ++j) { const f32x4 gg = gr[64 * j]; u32x2 o; o.x = cvt_pk_bf16(v0[j].x * r0 * gg.x, v0[j].y * r0 * gg.y); o.y = cvt_pk_bf16(v0[j].z * r0 * gg.z, v0[j].w * r0 * gg.w); o0[64 * j] = o;
;         u32x2 q; q.x = cvt_pk_bf16(v1[j].x * r1 * gg.x, v1[j].y * r1 * gg.y); q.y = cvt_pk_bf16(v1[j].z * r1 * gg.z, v1[j].w * r1 * gg.w); o1[64 * j] = q; }
; __device__ __forceinline__ void phase_p0(const Ctx& C, int l, const float* xin) {
;     ...
;     for (int row = gw; row < M_TOK; row += 2 * NGW) rms_row2_bf16(xin + (size_t)row * 1024, (size_t)NGW * 1024, C.P->in[1] + l * 1024, C.bfp(OFF_H) + (size_t)row * 1024, C.lane);
.LBB0_43:
	v_readlane_b32 s68, v251, 52
	s_lshl_b64 s[4:5], s[4:5], 2
	v_readlane_b32 s82, v252, 2
	v_readlane_b32 s69, v251, 53
	v_readlane_b32 s70, v251, 54
	v_readlane_b32 s71, v251, 55
	v_readlane_b32 s72, v251, 56
	v_readlane_b32 s73, v251, 57
	v_readlane_b32 s74, v251, 58
	v_readlane_b32 s75, v251, 59
	v_readlane_b32 s76, v251, 60
	v_readlane_b32 s77, v251, 61
	v_readlane_b32 s78, v251, 62
	v_readlane_b32 s79, v251, 63
	v_readlane_b32 s80, v252, 0
	v_readlane_b32 s81, v252, 1
	v_readlane_b32 s83, v252, 3
	s_add_u32 s7, s82, s4
	s_addc_u32 s10, s83, s5
	v_readlane_b32 s68, v251, 4
	s_and_b64 s[4:5], s[0:1], exec
	v_readlane_b32 s69, v251, 5
	s_cselect_b32 s5, s69, s10
	s_cselect_b32 s4, s68, s7
	v_writelane_b32 v254, s4, 61
	v_readlane_b32 s70, v251, 6
	v_readlane_b32 s71, v251, 7
	v_writelane_b32 v254, s5, 62
	v_readlane_b32 s72, v251, 8
	v_readlane_b32 s4, v254, 59
	v_readlane_b32 s5, v254, 60
	s_lshl_b32 s4, s4, 10
	s_mov_b32 s5, s37
	s_cmpk_gt_i32 s6, 0x7fff
	v_writelane_b32 v254, s4, 63
	v_readlane_b32 s73, v251, 9
	v_readlane_b32 s74, v251, 10
	v_writelane_b32 v255, s5, 0
	v_readlane_b32 s75, v251, 11
	v_readlane_b32 s76, v251, 12
	v_readlane_b32 s77, v251, 13
	v_readlane_b32 s78, v251, 14
	v_readlane_b32 s79, v251, 15
	v_readlane_b32 s80, v251, 16
	v_readlane_b32 s81, v251, 17
	v_readlane_b32 s82, v251, 18
	v_readlane_b32 s83, v251, 19
	s_cbranch_scc1 .LBB0_46
	v_and_b32_e32 v1, 64, v221
	v_add_u32_e32 v1, 64, v1
	v_xor_b32_e32 v2, 1, v221
	v_cmp_lt_i32_e32 vcc, v2, v1
	v_readlane_b32 s4, v254, 63
	v_readlane_b32 s5, v255, 0
	v_cndmask_b32_e32 v2, v221, v2, vcc
	v_lshlrev_b32_e32 v18, 2, v2
	v_xor_b32_e32 v2, 2, v221
	v_cmp_lt_i32_e32 vcc, v2, v1
	v_readlane_b32 s68, v251, 4
	s_lshl_b64 s[4:5], s[4:5], 2
	v_cndmask_b32_e32 v2, v221, v2, vcc
	v_lshlrev_b32_e32 v19, 2, v2
	v_xor_b32_e32 v2, 4, v221
	v_cmp_lt_i32_e32 vcc, v2, v1
	v_readlane_b32 s70, v251, 6
	v_readlane_b32 s71, v251, 7
	v_cndmask_b32_e32 v2, v221, v2, vcc
	v_lshlrev_b32_e32 v20, 2, v2
	v_xor_b32_e32 v2, 8, v221
	v_cmp_lt_i32_e32 vcc, v2, v1
	s_add_u32 s4, s70, s4
	s_addc_u32 s5, s71, s5
	v_cndmask_b32_e32 v2, v221, v2, vcc
	v_lshlrev_b32_e32 v21, 2, v2
	v_xor_b32_e32 v2, 16, v221
	v_lshlrev_b32_e32 v64, 4, v3
	v_cmp_lt_i32_e32 vcc, v2, v1
	s_ashr_i32 s7, s6, 31
	v_lshl_add_u64 v[12:13], s[4:5], 0, v[64:65]
	v_cndmask_b32_e32 v2, v221, v2, vcc
	s_lshl_b64 s[4:5], s[6:7], 11
	v_lshlrev_b32_e32 v22, 2, v2
	v_xor_b32_e32 v2, 32, v221
	s_add_u32 s4, s8, s4
	v_cmp_lt_i32_e32 vcc, v2, v1
	s_addc_u32 s5, s9, s5
	s_add_u32 s4, s24, s4
	v_cndmask_b32_e32 v1, v221, v2, vcc
	v_lshlrev_b32_e32 v23, 2, v1
	v_mov_b32_e32 v1, v65
	s_addc_u32 s5, s25, s5
	v_lshl_add_u64 v[14:15], s[4:5], 0, v[0:1]
	s_lshl_b64 s[4:5], s[6:7], 12
	v_readlane_b32 s8, v254, 61
	v_readlane_b32 s9, v254, 62
	s_add_u32 s4, s8, s4
	s_addc_u32 s5, s9, s5
	v_readlane_b32 s10, v254, 18
	v_readlane_b32 s12, v254, 22
	v_lshl_add_u64 v[16:17], s[4:5], 0, v[64:65]
	v_readlane_b32 s8, v254, 16
	v_readlane_b32 s11, v254, 19
	v_readlane_b32 s13, v254, 23
	s_mov_b32 s14, 0x3a800000
	v_readlane_b32 s69, v251, 5
	v_readlane_b32 s72, v251, 8
	v_readlane_b32 s73, v251, 9
	v_readlane_b32 s74, v251, 10
	v_readlane_b32 s75, v251, 11
	v_readlane_b32 s76, v251, 12
	v_readlane_b32 s77, v251, 13
	v_readlane_b32 s78, v251, 14
	v_readlane_b32 s79, v251, 15
	v_readlane_b32 s80, v251, 16
	v_readlane_b32 s81, v251, 17
	v_readlane_b32 s82, v251, 18
	v_readlane_b32 s83, v251, 19
	v_readlane_b32 s9, v254, 17
	global_load_dwordx4 v[112:115], v[12:13], off offset:1024
	global_load_dwordx4 v[116:119], v[12:13], off offset:2048
	global_load_dwordx4 v[120:123], v[12:13], off offset:3072
	s_waitcnt vmcnt(0)
; __device__ __forceinline__ unsigned cvt_pk_bf16(float lo, float hi) { f32x2_t v = {lo, hi}; bf2_t r = __builtin_convertvector(v, bf2_t); return __builtin_bit_cast(unsigned, r); }
; __device__ __forceinline__ void rms_row2_bf16(const float* xrow, size_t stride, const float* g, bf16_t* orow, int lane) {
;     const f32x4* xr0 = (const f32x4*)xrow + lane; const f32x4* xr1 = (const f32x4*)(xrow + stride) + lane; const f32x4* gr = (const f32x4*)g + lane;
;     f32x4 v0[4], v1[4]; float s0 = 0.f, s1 = 0.f;
; #pragma unroll
;     for (int j = 0; j < 4; ++j) { v0[j] = xr0[64 * j]; v1[j] = xr1[64 * j]; }
; #pragma unroll
;     for (int j = 0; j < 4; ++j) { s0 += (v0[j].x * v0[j].x + v0[j].y * v0[j].y) + (v0[j].z * v0[j].z + v0[j].w * v0[j].w); s1 += (v1[j].x * v1[j].x + v1[j].y * v1[j].y) + (v1[j].z * v1[j].z + v1[j].w * v1[j].w); }
;     const float r0 = rsqrtf(wave_sum(s0) * (1.f / 1024.f) + 1e-6f), r1 = rsqrtf(wave_sum(s1) * (1.f / 1024.f) + 1e-6f);
;     u32x2* o0 = (u32x2*)orow + lane; u32x2* o1 = (u32x2*)(orow + stride) + lane;
; #pragma unroll
;     for (int j = 0; j < 4; ++j) { const f32x4 gg = gr[64 * j]; u32x2 o; o.x = cvt_pk_bf16(v0[j].x * r0 * gg.x, v0[j].y * r0 * gg.y); o.y = cvt_pk_bf16(v0[j].z * r0 * gg.z, v0[j].w * r0 * gg.w); o0[64 * j] = o;
;         u32x2 q; q.x = cvt_pk_bf16(v1[j].x * r1 * gg.x, v1[j].y * r1 * gg.y); q.y = cvt_pk_bf16(v1[j].z * r1 * gg.z, v1[j].w * r1 * gg.w); o1[64 * j] = q; }
.LBB0_45:
	global_load_dwordx4 v[24:27], v[16:17], off
	global_load_dwordx4 v[8:11], v[16:17], off offset:1024
	global_load_dwordx4 v[0:3], v[16:17], off offset:3072
	global_load_dwordx4 v[4:7], v[16:17], off offset:2048
	v_lshl_add_u64 v[44:45], v[16:17], 0, s[52:53]
	global_load_dwordx4 v[28:31], v[12:13], off
	global_load_dwordx4 v[32:35], v[44:45], off
	global_load_dwordx4 v[36:39], v[44:45], off offset:1024
	global_load_dwordx4 v[40:43], v[44:45], off offset:3072
	s_nop 0
	global_load_dwordx4 v[44:47], v[44:45], off offset:2048
	v_lshl_add_u64 v[48:49], v[14:15], 0, s[12:13]
	s_add_i32 s6, s6, s8
	v_lshl_add_u64 v[16:17], v[16:17], 0, s[10:11]
	s_cmp_lt_i32 s6, 0x8000
	s_waitcnt vmcnt(8)
	v_pk_mul_f32 v[50:51], v[26:27], v[26:27]
	v_pk_mul_f32 v[52:53], v[24:25], v[24:25]
	s_waitcnt vmcnt(7)
	v_pk_mul_f32 v[54:55], v[10:11], v[10:11]
	v_pk_mul_f32 v[56:57], v[8:9], v[8:9]
	s_waitcnt vmcnt(5)
	v_mul_f32_e32 v58, v5, v5
	v_mul_f32_e32 v60, v7, v7
	v_pk_mov_b32 v[62:63], v[52:53], v[50:51] op_sel:[1,0]
	v_mov_b32_e32 v53, v51
	s_waitcnt vmcnt(3)
	v_pk_mul_f32 v[50:51], v[34:35], v[34:35]
	v_pk_mul_f32 v[66:67], v[32:33], v[32:33]
	v_pk_mov_b32 v[68:69], v[56:57], v[54:55] op_sel:[1,0]
	v_mov_b32_e32 v57, v55
	s_waitcnt vmcnt(2)
	v_pk_mul_f32 v[54:55], v[38:39], v[38:39]
	v_pk_mul_f32 v[70:71], v[36:37], v[36:37]
	v_mul_f32_e32 v75, v2, v2
	v_mul_f32_e32 v76, v3, v3
	v_pk_fma_f32 v[58:59], v[4:5], v[4:5], v[58:59] op_sel_hi:[1,1,0]
	v_pk_fma_f32 v[60:61], v[6:7], v[6:7], v[60:61] op_sel_hi:[1,1,0]
	v_pk_add_f32 v[52:53], v[62:63], v[52:53]
	v_pk_mov_b32 v[62:63], v[66:67], v[50:51] op_sel:[1,0]
	v_mov_b32_e32 v67, v51
	v_pk_add_f32 v[50:51], v[68:69], v[56:57]
	v_pk_mov_b32 v[56:57], v[70:71], v[54:55] op_sel:[1,0]
	v_mov_b32_e32 v71, v55
	v_mul_f32_e32 v73, v0, v0
	s_waitcnt vmcnt(0)
	v_mul_f32_e32 v64, v45, v45
	v_mul_f32_e32 v72, v47, v47
	v_mov_b32_e32 v59, v75
	v_mov_b32_e32 v61, v76
	v_pk_add_f32 v[62:63], v[62:63], v[66:67]
	v_pk_add_f32 v[56:57], v[56:57], v[70:71]
	v_mul_f32_e32 v74, v1, v1
	v_mul_f32_e32 v77, v40, v40
	v_mul_f32_e32 v78, v41, v41
	v_mul_f32_e32 v79, v42, v42
	v_mul_f32_e32 v80, v43, v43
	v_pk_fma_f32 v[54:55], v[44:45], v[44:45], v[64:65] op_sel_hi:[1,1,0]
	v_pk_fma_f32 v[68:69], v[46:47], v[46:47], v[72:73] op_sel_hi:[1,1,0]
	v_pk_add_f32 v[52:53], v[52:53], v[52:53] op_sel:[0,1] op_sel_hi:[1,0]
	v_pk_add_f32 v[50:51], v[50:51], v[50:51] op_sel:[0,1] op_sel_hi:[1,0]
	v_pk_add_f32 v[58:59], v[58:59], v[60:61]
	v_pk_add_f32 v[60:61], v[62:63], v[62:63] op_sel:[0,1] op_sel_hi:[1,0]
	v_pk_add_f32 v[56:57], v[56:57], v[56:57] op_sel:[0,1] op_sel_hi:[1,0]
	v_mov_b32_e32 v55, v79
	v_mov_b32_e32 v69, v80
	v_mov_b32_e32 v53, v73
	v_mov_b32_e32 v51, v74
	v_mov_b32_e32 v61, v77
	v_mov_b32_e32 v57, v78
	v_pk_add_f32 v[54:55], v[54:55], v[68:69]
	v_pk_add_f32 v[50:51], v[52:53], v[50:51]
	v_pk_add_f32 v[52:53], v[60:61], v[56:57]
	v_pk_add_f32 v[50:51], v[50:51], v[58:59]
	v_pk_add_f32 v[52:53], v[52:53], v[54:55]
	v_mov_b32_e32 v55, v50
	v_mov_b32_e32 v54, v52
	v_mov_b32_e32 v50, v53
	v_pk_add_f32 v[50:51], v[54:55], v[50:51]
	ds_bpermute_b32 v53, v18, v51
	ds_bpermute_b32 v52, v18, v50
	s_waitcnt lgkmcnt(0)
	v_pk_add_f32 v[50:51], v[50:51], v[52:53]
	ds_bpermute_b32 v53, v19, v51
	ds_bpermute_b32 v52, v19, v50
	s_waitcnt lgkmcnt(0)
	v_pk_add_f32 v[50:51], v[50:51], v[52:53]
	ds_bpermute_b32 v53, v20, v51
	ds_bpermute_b32 v52, v20, v50
	s_waitcnt lgkmcnt(0)
	v_pk_add_f32 v[50:51], v[50:51], v[52:53]
	ds_bpermute_b32 v53, v21, v51
	ds_bpermute_b32 v52, v21, v50
	s_waitcnt lgkmcnt(0)
	v_pk_add_f32 v[50:51], v[50:51], v[52:53]
	ds_bpermute_b32 v53, v22, v51
	ds_bpermute_b32 v52, v22, v50
	s_waitcnt lgkmcnt(0)
	v_pk_add_f32 v[50:51], v[50:51], v[52:53]
	ds_bpermute_b32 v53, v23, v51
	ds_bpermute_b32 v52, v23, v50
	s_waitcnt lgkmcnt(0)
	v_pk_add_f32 v[50:51], v[50:51], v[52:53]
	s_nop 0
	v_pk_fma_f32 v[50:51], v[50:51], s[14:15], v[238:239] op_sel_hi:[1,0,0]
	s_nop 0
	v_mul_f32_e32 v52, 0x4b800000, v51
	v_cmp_gt_f32_e64 s[4:5], s54, v51
	v_mul_f32_e32 v53, 0x4b800000, v50
	v_cmp_gt_f32_e32 vcc, s54, v50
	v_cndmask_b32_e64 v51, v51, v52, s[4:5]
	v_rsq_f32_e32 v51, v51
	v_cndmask_b32_e32 v50, v50, v53, vcc
	v_rsq_f32_e32 v52, v50
	v_mul_f32_e32 v50, 0x45800000, v51
	v_cndmask_b32_e64 v50, v51, v50, s[4:5]
	v_mul_f32_e32 v53, 0x45800000, v52
	v_cndmask_b32_e32 v52, v52, v53, vcc
	v_pk_mul_f32 v[24:25], v[24:25], v[50:51] op_sel_hi:[1,0]
	v_pk_mul_f32 v[26:27], v[26:27], v[50:51] op_sel_hi:[1,0]
	v_pk_mul_f32 v[32:33], v[32:33], v[52:53] op_sel_hi:[1,0]
	v_pk_mul_f32 v[34:35], v[34:35], v[52:53] op_sel_hi:[1,0]
	v_pk_mul_f32 v[24:25], v[28:29], v[24:25]
	v_pk_mul_f32 v[26:27], v[30:31], v[26:27]
	v_pk_mul_f32 v[28:29], v[28:29], v[32:33]
	v_pk_mul_f32 v[30:31], v[30:31], v[34:35]
	v_cvt_pk_bf16_f32 v24, v24, v25
	v_cvt_pk_bf16_f32 v25, v26, v27
	v_cvt_pk_bf16_f32 v26, v28, v29
	v_cvt_pk_bf16_f32 v27, v30, v31
	global_store_dwordx2 v[14:15], v[24:25], off
	global_store_dwordx2 v[48:49], v[26:27], off
	v_pk_mul_f32 v[8:9], v[8:9], v[50:51] op_sel_hi:[1,0]
	v_pk_mul_f32 v[10:11], v[10:11], v[50:51] op_sel_hi:[1,0]
	v_pk_mul_f32 v[28:29], v[36:37], v[52:53] op_sel_hi:[1,0]
	v_pk_mul_f32 v[30:31], v[38:39], v[52:53] op_sel_hi:[1,0]
	v_pk_mul_f32 v[4:5], v[4:5], v[50:51] op_sel_hi:[1,0]
	v_pk_mul_f32 v[6:7], v[6:7], v[50:51] op_sel_hi:[1,0]
	v_pk_mul_f32 v[0:1], v[0:1], v[50:51] op_sel_hi:[1,0]
	v_pk_mul_f32 v[2:3], v[2:3], v[50:51] op_sel_hi:[1,0]
	v_pk_mul_f32 v[8:9], v[112:113], v[8:9]
	v_pk_mul_f32 v[10:11], v[114:115], v[10:11]
	v_pk_mul_f32 v[24:25], v[112:113], v[28:29]
	v_pk_mul_f32 v[26:27], v[114:115], v[30:31]
	v_cvt_pk_bf16_f32 v8, v8, v9
	v_cvt_pk_bf16_f32 v9, v10, v11
	v_cvt_pk_bf16_f32 v10, v24, v25
	v_cvt_pk_bf16_f32 v11, v26, v27
	global_store_dwordx2 v[14:15], v[8:9], off offset:512
	global_store_dwordx2 v[48:49], v[10:11], off offset:512
	v_pk_mul_f32 v[24:25], v[44:45], v[52:53] op_sel_hi:[1,0]
	v_pk_mul_f32 v[26:27], v[46:47], v[52:53] op_sel_hi:[1,0]
	v_pk_mul_f32 v[4:5], v[4:5], v[116:117]
	v_pk_mul_f32 v[6:7], v[6:7], v[118:119]
	v_pk_mul_f32 v[8:9], v[116:117], v[24:25]
	v_pk_mul_f32 v[10:11], v[118:119], v[26:27]
	v_cvt_pk_bf16_f32 v4, v4, v5
	v_cvt_pk_bf16_f32 v5, v6, v7
	v_cvt_pk_bf16_f32 v6, v8, v9
	v_cvt_pk_bf16_f32 v7, v10, v11
	global_store_dwordx2 v[14:15], v[4:5], off offset:1024
	global_store_dwordx2 v[48:49], v[6:7], off offset:1024
	v_pk_mul_f32 v[8:9], v[40:41], v[52:53] op_sel_hi:[1,0]
	v_pk_mul_f32 v[10:11], v[42:43], v[52:53] op_sel_hi:[1,0]
	v_pk_mul_f32 v[0:1], v[0:1], v[120:121]
	v_pk_mul_f32 v[2:3], v[2:3], v[122:123]
	v_pk_mul_f32 v[4:5], v[8:9], v[120:121]
	v_pk_mul_f32 v[6:7], v[10:11], v[122:123]
	v_cvt_pk_bf16_f32 v0, v0, v1
	v_cvt_pk_bf16_f32 v1, v2, v3
	v_cvt_pk_bf16_f32 v2, v4, v5
	v_cvt_pk_bf16_f32 v3, v6, v7
	global_store_dwordx2 v[14:15], v[0:1], off offset:1536
	global_store_dwordx2 v[48:49], v[2:3], off offset:1536
	v_lshl_add_u64 v[14:15], v[14:15], 0, s[40:41]
	s_cbranch_scc1 .LBB0_45

; __device__ __forceinline__ unsigned cvt_pk_bf16(float lo, float hi) { f32x2_t v = {lo, hi}; bf2_t r = __builtin_convertvector(v, bf2_t); return __builtin_bit_cast(unsigned, r); }
;     __device__ __forceinline__ bf16_t* bfp(size_t off) const { return (bf16_t*)(ws + off); }
; #define FRESH() do { int _t = threadIdx.x; asm volatile("" : "+v"(_t)); C.tid = _t; C.lane = _t & 63; C.wave = __builtin_amdgcn_readfirstlane(_t >> 6); size_t _z = 0; asm volatile("" : "+s"(_z)); C.ws = prm.ws + _z; C.out = prm.out + _z; } while (0)
; __device__ __forceinline__ void rms_row2_bf16(const float* xrow, size_t stride, const float* g, bf16_t* orow, int lane) {
;     const f32x4* xr0 = (const f32x4*)xrow + lane; const f32x4* xr1 = (const f32x4*)(xrow + stride) + lane; const f32x4* gr = (const f32x4*)g + lane;
;     f32x4 v0[4], v1[4]; float s0 = 0.f, s1 = 0.f;
; #pragma unroll
;     for (int j = 0; j < 4; ++j) { v0[j] = xr0[64 * j]; v1[j] = xr1[64 * j]; }
; #pragma unroll
;     for (int j = 0; j < 4; ++j) { s0 += (v0[j].x * v0[j].x + v0[j].y * v0[j].y) + (v0[j].z * v0[j].z + v0[j].w * v0[j].w); s1 += (v1[j].x * v1[j].x + v1[j].y * v1[j].y) + (v1[j].z * v1[j].z + v1[j].w * v1[j].w); }
;     const float r0 = rsqrtf(wave_sum(s0) * (1.f / 1024.f) + 1e-6f), r1 = rsqrtf(wave_sum(s1) * (1.f / 1024.f) + 1e-6f);
;     u32x2* o0 = (u32x2*)orow + lane; u32x2* o1 = (u32x2*)(orow + stride) + lane;
; #pragma unroll
;     for (int j = 0; j < 4; ++j) { const f32x4 gg = gr[64 * j]; u32x2 o; o.x = cvt_pk_bf16(v0[j].x * r0 * gg.x, v0[j].y * r0 * gg.y); o.y = cvt_pk_bf16(v0[j].z * r0 * gg.z, v0[j].w * r0 * gg.w); o0[64 * j] = o;
;         u32x2 q; q.x = cvt_pk_bf16(v1[j].x * r1 * gg.x, v1[j].y * r1 * gg.y); q.y = cvt_pk_bf16(v1[j].z * r1 * gg.z, v1[j].w * r1 * gg.w); o1[64 * j] = q; }
; __global__ void __launch_bounds__(NTHR, 2) fwd_megakernel(Params prm) {
;     ...
;         FRESH();
;         for (int row = bid * 8 + C.wave; row < M_TOK; row += 2 * G * 8) rms_row2_bf16(C.out + (size_t)row * 1024, (size_t)G * 8 * 1024, C.P->in[26] + l * 1024, C.bfp(OFF_H) + (size_t)row * 1024, C.lane);
.LBB0_1062:
	s_or_b64 exec, exec, s[0:1]
	s_waitcnt lgkmcnt(0)
	v_mov_b32_e32 v0, v224
	s_barrier
	s_mov_b64 s[0:1], 0
	v_mov_b32_e32 v0, v224
	v_readlane_b32 s5, v253, 32
	v_readfirstlane_b32 s0, v0
	s_ashr_i32 s4, s0, 6
	s_add_i32 s4, s4, s5
	s_mov_b64 s[0:1], 0
	s_cmpk_gt_i32 s4, 0x7fff
	v_readlane_b32 s30, v254, 16
	v_readlane_b32 s31, v254, 17
	s_cbranch_scc1 .LBB0_1065
	v_and_b32_e32 v1, 64, v221
	v_add_u32_e32 v1, 64, v1
	v_xor_b32_e32 v2, 1, v221
	v_cmp_lt_i32_e32 vcc, v2, v1
	v_readlane_b32 s6, v254, 63
	v_readlane_b32 s7, v255, 0
	v_cndmask_b32_e32 v2, v221, v2, vcc
	v_lshlrev_b32_e32 v43, 2, v2
	v_xor_b32_e32 v2, 2, v221
	v_cmp_lt_i32_e32 vcc, v2, v1
	v_readlane_b32 s8, v251, 52
	s_lshl_b64 s[6:7], s[6:7], 2
	v_cndmask_b32_e32 v2, v221, v2, vcc
	v_lshlrev_b32_e32 v45, 2, v2
	v_xor_b32_e32 v2, 4, v221
	v_cmp_lt_i32_e32 vcc, v2, v1
	v_readlane_b32 s12, v251, 56
	v_and_b32_e32 v0, 63, v0
	v_cndmask_b32_e32 v2, v221, v2, vcc
	v_lshlrev_b32_e32 v48, 2, v2
	v_xor_b32_e32 v2, 8, v221
	v_cmp_lt_i32_e32 vcc, v2, v1
	v_readlane_b32 s13, v251, 57
	s_add_u32 s6, s12, s6
	v_cndmask_b32_e32 v2, v221, v2, vcc
	v_lshlrev_b32_e32 v49, 2, v2
	v_xor_b32_e32 v2, 16, v221
	s_addc_u32 s7, s13, s7
	v_lshlrev_b32_e32 v64, 4, v0
	v_cmp_lt_i32_e32 vcc, v2, v1
	s_ashr_i32 s5, s4, 31
	v_lshl_add_u64 v[36:37], s[6:7], 0, v[64:65]
	v_cndmask_b32_e32 v2, v221, v2, vcc
	s_lshl_b64 s[6:7], s[4:5], 11
	v_lshlrev_b32_e32 v50, 2, v2
	v_xor_b32_e32 v2, 32, v221
	s_add_u32 s6, s0, s6
	v_cmp_lt_i32_e32 vcc, v2, v1
	s_addc_u32 s7, s1, s7
	s_add_u32 s6, s24, s6
	v_cndmask_b32_e32 v1, v221, v2, vcc
	v_lshlrev_b32_e32 v51, 2, v1
	v_lshlrev_b32_e32 v0, 3, v0
	v_mov_b32_e32 v1, v65
	s_addc_u32 s7, s25, s7
	v_readlane_b32 s22, v252, 2
	v_lshl_add_u64 v[38:39], s[6:7], 0, v[0:1]
	s_lshl_b64 s[6:7], s[4:5], 12
	s_lshl_b64 s[0:1], s[0:1], 2
	v_readlane_b32 s23, v252, 3
	s_add_u32 s0, s22, s0
	s_addc_u32 s1, s23, s1
	s_add_u32 s0, s0, s6
	s_addc_u32 s1, s1, s7
	v_lshl_add_u64 v[40:41], s[0:1], 0, v[64:65]
	v_readlane_b32 s9, v251, 53
	v_readlane_b32 s10, v251, 54
	v_readlane_b32 s11, v251, 55
	v_readlane_b32 s14, v251, 58
	v_readlane_b32 s15, v251, 59
	v_readlane_b32 s16, v251, 60
	v_readlane_b32 s17, v251, 61
	v_readlane_b32 s18, v251, 62
	v_readlane_b32 s19, v251, 63
	v_readlane_b32 s20, v252, 0
	v_readlane_b32 s21, v252, 1
	global_load_dwordx4 v[112:115], v[36:37], off
	global_load_dwordx4 v[116:119], v[36:37], off offset:1024
	global_load_dwordx4 v[120:123], v[36:37], off offset:2048
	global_load_dwordx4 v[124:127], v[36:37], off offset:3072
	s_waitcnt vmcnt(0)
; __device__ __forceinline__ unsigned cvt_pk_bf16(float lo, float hi) { f32x2_t v = {lo, hi}; bf2_t r = __builtin_convertvector(v, bf2_t); return __builtin_bit_cast(unsigned, r); }
; __device__ __forceinline__ void rms_row2_bf16(const float* xrow, size_t stride, const float* g, bf16_t* orow, int lane) {
;     const f32x4* xr0 = (const f32x4*)xrow + lane; const f32x4* xr1 = (const f32x4*)(xrow + stride) + lane; const f32x4* gr = (const f32x4*)g + lane;
;     f32x4 v0[4], v1[4]; float s0 = 0.f, s1 = 0.f;
; #pragma unroll
;     for (int j = 0; j < 4; ++j) { v0[j] = xr0[64 * j]; v1[j] = xr1[64 * j]; }
; #pragma unroll
;     for (int j = 0; j < 4; ++j) { s0 += (v0[j].x * v0[j].x + v0[j].y * v0[j].y) + (v0[j].z * v0[j].z + v0[j].w * v0[j].w); s1 += (v1[j].x * v1[j].x + v1[j].y * v1[j].y) + (v1[j].z * v1[j].z + v1[j].w * v1[j].w); }
;     const float r0 = rsqrtf(wave_sum(s0) * (1.f / 1024.f) + 1e-6f), r1 = rsqrtf(wave_sum(s1) * (1.f / 1024.f) + 1e-6f);
;     u32x2* o0 = (u32x2*)orow + lane; u32x2* o1 = (u32x2*)(orow + stride) + lane;
; #pragma unroll
;     for (int j = 0; j < 4; ++j) { const f32x4 gg = gr[64 * j]; u32x2 o; o.x = cvt_pk_bf16(v0[j].x * r0 * gg.x, v0[j].y * r0 * gg.y); o.y = cvt_pk_bf16(v0[j].z * r0 * gg.z, v0[j].w * r0 * gg.w); o0[64 * j] = o;
;         u32x2 q; q.x = cvt_pk_bf16(v1[j].x * r1 * gg.x, v1[j].y * r1 * gg.y); q.y = cvt_pk_bf16(v1[j].z * r1 * gg.z, v1[j].w * r1 * gg.w); o1[64 * j] = q; }
; }
.LBB0_1064:
	v_lshl_add_u64 v[0:1], v[40:41], 0, s[42:43]
	global_load_dwordx4 v[28:31], v[40:41], off
	global_load_dwordx4 v[24:27], v[0:1], off
	global_load_dwordx4 v[20:23], v[40:41], off offset:1024
	global_load_dwordx4 v[16:19], v[0:1], off offset:1024
	global_load_dwordx4 v[12:15], v[40:41], off offset:2048
	global_load_dwordx4 v[8:11], v[0:1], off offset:2048
	global_load_dwordx4 v[4:7], v[40:41], off offset:3072
	s_nop 0
	global_load_dwordx4 v[0:3], v[0:1], off offset:3072
	s_add_i32 s4, s4, s30
	v_lshl_add_u64 v[40:41], v[40:41], 0, s[38:39]
	s_cmpk_gt_i32 s4, 0x7fff
	s_waitcnt vmcnt(7)
	v_pk_mul_f32 v[32:33], v[30:31], v[30:31]
	v_pk_mul_f32 v[34:35], v[28:29], v[28:29]
	s_waitcnt vmcnt(1)
	v_mul_f32_e32 v42, v4, v4
	v_pk_mov_b32 v[46:47], v[34:35], v[32:33] op_sel:[1,0]
	v_mov_b32_e32 v35, v33
	v_pk_add_f32 v[32:33], v[46:47], v[34:35]
	v_pk_mul_f32 v[34:35], v[26:27], v[26:27]
	v_pk_mul_f32 v[46:47], v[24:25], v[24:25]
	v_mul_f32_e32 v44, v5, v5
	v_pk_mov_b32 v[52:53], v[46:47], v[34:35] op_sel:[1,0]
	v_mov_b32_e32 v47, v35
	v_pk_add_f32 v[34:35], v[52:53], v[46:47]
	v_pk_mul_f32 v[46:47], v[22:23], v[22:23]
	v_pk_mul_f32 v[52:53], v[20:21], v[20:21]
	v_pk_add_f32 v[32:33], v[32:33], v[32:33] op_sel:[0,1] op_sel_hi:[1,0]
	v_pk_mov_b32 v[54:55], v[52:53], v[46:47] op_sel:[1,0]
	v_mov_b32_e32 v53, v47
	v_pk_add_f32 v[46:47], v[54:55], v[52:53]
	v_pk_mul_f32 v[52:53], v[18:19], v[18:19]
	v_pk_mul_f32 v[54:55], v[16:17], v[16:17]
	v_pk_add_f32 v[46:47], v[46:47], v[46:47] op_sel:[0,1] op_sel_hi:[1,0]
	v_pk_mov_b32 v[56:57], v[54:55], v[52:53] op_sel:[1,0]
	v_mov_b32_e32 v55, v53
	v_mov_b32_e32 v33, v42
	v_mov_b32_e32 v47, v44
	v_mul_f32_e32 v42, v13, v13
	v_pk_add_f32 v[52:53], v[56:57], v[54:55]
	v_mul_f32_e32 v54, v6, v6
	v_pk_add_f32 v[32:33], v[32:33], v[46:47]
	v_pk_fma_f32 v[46:47], v[12:13], v[12:13], v[42:43] op_sel_hi:[1,1,0]
	v_mul_f32_e32 v42, v15, v15
	v_mul_f32_e32 v56, v7, v7
	v_mov_b32_e32 v47, v54
	v_pk_fma_f32 v[54:55], v[14:15], v[14:15], v[42:43] op_sel_hi:[1,1,0]
	s_waitcnt vmcnt(0)
	v_mul_f32_e32 v42, v0, v0
	v_mov_b32_e32 v55, v56
	v_pk_add_f32 v[46:47], v[46:47], v[54:55]
	v_mul_f32_e32 v44, v1, v1
	v_pk_add_f32 v[32:33], v[32:33], v[46:47]
	v_pk_add_f32 v[34:35], v[34:35], v[34:35] op_sel:[0,1] op_sel_hi:[1,0]
	v_pk_add_f32 v[46:47], v[52:53], v[52:53] op_sel:[0,1] op_sel_hi:[1,0]
	v_mov_b32_e32 v35, v42
	v_mov_b32_e32 v47, v44
	v_mul_f32_e32 v42, v9, v9
	v_pk_add_f32 v[34:35], v[34:35], v[46:47]
	v_pk_fma_f32 v[46:47], v[8:9], v[8:9], v[42:43] op_sel_hi:[1,1,0]
	v_mul_f32_e32 v42, v11, v11
	v_mul_f32_e32 v54, v2, v2
	v_mul_f32_e32 v55, v3, v3
	v_pk_fma_f32 v[52:53], v[10:11], v[10:11], v[42:43] op_sel_hi:[1,1,0]
	v_mov_b32_e32 v47, v54
	v_mov_b32_e32 v53, v55
	v_pk_add_f32 v[46:47], v[46:47], v[52:53]
	s_nop 0
	v_pk_add_f32 v[34:35], v[34:35], v[46:47]
	v_mov_b32_e32 v47, v32
	v_mov_b32_e32 v46, v34
	v_mov_b32_e32 v32, v35
	v_pk_add_f32 v[32:33], v[46:47], v[32:33]
	ds_bpermute_b32 v35, v43, v33
	ds_bpermute_b32 v34, v43, v32
	v_lshl_add_u64 v[46:47], v[38:39], 0, s[44:45]
	s_waitcnt lgkmcnt(0)
	v_pk_add_f32 v[32:33], v[32:33], v[34:35]
	ds_bpermute_b32 v35, v45, v33
	ds_bpermute_b32 v34, v45, v32
	s_waitcnt lgkmcnt(0)
	v_pk_add_f32 v[32:33], v[32:33], v[34:35]
	ds_bpermute_b32 v35, v48, v33
	ds_bpermute_b32 v34, v48, v32
	s_waitcnt lgkmcnt(0)
	v_pk_add_f32 v[32:33], v[32:33], v[34:35]
	ds_bpermute_b32 v35, v49, v33
	ds_bpermute_b32 v34, v49, v32
	s_waitcnt lgkmcnt(0)
	v_pk_add_f32 v[32:33], v[32:33], v[34:35]
	ds_bpermute_b32 v35, v50, v33
	ds_bpermute_b32 v34, v50, v32
	s_waitcnt lgkmcnt(0)
	v_pk_add_f32 v[32:33], v[32:33], v[34:35]
	ds_bpermute_b32 v35, v51, v33
	ds_bpermute_b32 v34, v51, v32
	s_waitcnt lgkmcnt(0)
	v_pk_add_f32 v[32:33], v[32:33], v[34:35]
	s_nop 0
	v_pk_fma_f32 v[32:33], v[32:33], s[36:37], v[238:239] op_sel_hi:[1,0,0]
	s_nop 0
	v_mul_f32_e32 v34, 0x4b800000, v33
	v_cmp_gt_f32_e64 s[0:1], s54, v33
	v_cmp_gt_f32_e32 vcc, s54, v32
	s_nop 0
	v_cndmask_b32_e64 v33, v33, v34, s[0:1]
	v_rsq_f32_e32 v33, v33
	s_nop 0
	v_mul_f32_e32 v34, 0x45800000, v33
	v_cndmask_b32_e64 v44, v33, v34, s[0:1]
	v_mul_f32_e32 v33, 0x4b800000, v32
	v_cndmask_b32_e32 v32, v32, v33, vcc
	v_rsq_f32_e32 v32, v32
	v_pk_mul_f32 v[28:29], v[28:29], v[44:45] op_sel_hi:[1,0]
	v_pk_mul_f32 v[30:31], v[30:31], v[44:45] op_sel_hi:[1,0]
	v_pk_mul_f32 v[20:21], v[20:21], v[44:45] op_sel_hi:[1,0]
	v_mul_f32_e32 v33, 0x45800000, v32
	v_cndmask_b32_e32 v42, v32, v33, vcc
	v_pk_mul_f32 v[24:25], v[24:25], v[42:43] op_sel_hi:[1,0]
	v_pk_mul_f32 v[26:27], v[26:27], v[42:43] op_sel_hi:[1,0]
	v_pk_mul_f32 v[22:23], v[22:23], v[44:45] op_sel_hi:[1,0]
	v_pk_mul_f32 v[16:17], v[16:17], v[42:43] op_sel_hi:[1,0]
	v_pk_mul_f32 v[18:19], v[18:19], v[42:43] op_sel_hi:[1,0]
	v_pk_mul_f32 v[12:13], v[12:13], v[44:45] op_sel_hi:[1,0]
	v_pk_mul_f32 v[14:15], v[14:15], v[44:45] op_sel_hi:[1,0]
	v_pk_mul_f32 v[8:9], v[8:9], v[42:43] op_sel_hi:[1,0]
	v_pk_mul_f32 v[10:11], v[10:11], v[42:43] op_sel_hi:[1,0]
	v_pk_mul_f32 v[4:5], v[4:5], v[44:45] op_sel_hi:[1,0]
	v_pk_mul_f32 v[6:7], v[6:7], v[44:45] op_sel_hi:[1,0]
	v_pk_mul_f32 v[0:1], v[0:1], v[42:43] op_sel_hi:[1,0]
	v_pk_mul_f32 v[2:3], v[2:3], v[42:43] op_sel_hi:[1,0]
	v_pk_mul_f32 v[28:29], v[112:113], v[28:29]
	v_pk_mul_f32 v[30:31], v[114:115], v[30:31]
	v_pk_mul_f32 v[24:25], v[112:113], v[24:25]
	v_pk_mul_f32 v[26:27], v[114:115], v[26:27]
	v_cvt_pk_bf16_f32 v28, v28, v29
	v_cvt_pk_bf16_f32 v29, v30, v31
	v_cvt_pk_bf16_f32 v24, v24, v25
	v_cvt_pk_bf16_f32 v25, v26, v27
	global_store_dwordx2 v[38:39], v[28:29], off
	global_store_dwordx2 v[46:47], v[24:25], off
	v_pk_mul_f32 v[20:21], v[20:21], v[116:117]
	v_pk_mul_f32 v[22:23], v[22:23], v[118:119]
	v_pk_mul_f32 v[16:17], v[116:117], v[16:17]
	v_pk_mul_f32 v[18:19], v[118:119], v[18:19]
	v_cvt_pk_bf16_f32 v20, v20, v21
	v_cvt_pk_bf16_f32 v21, v22, v23
	v_cvt_pk_bf16_f32 v16, v16, v17
	v_cvt_pk_bf16_f32 v17, v18, v19
	global_store_dwordx2 v[38:39], v[20:21], off offset:512
	global_store_dwordx2 v[46:47], v[16:17], off offset:512
	v_pk_mul_f32 v[12:13], v[12:13], v[120:121]
	v_pk_mul_f32 v[14:15], v[14:15], v[122:123]
	v_pk_mul_f32 v[8:9], v[120:121], v[8:9]
	v_pk_mul_f32 v[10:11], v[122:123], v[10:11]
	v_cvt_pk_bf16_f32 v12, v12, v13
	v_cvt_pk_bf16_f32 v13, v14, v15
	v_cvt_pk_bf16_f32 v8, v8, v9
	v_cvt_pk_bf16_f32 v9, v10, v11
	global_store_dwordx2 v[38:39], v[12:13], off offset:1024
	global_store_dwordx2 v[46:47], v[8:9], off offset:1024
	v_pk_mul_f32 v[4:5], v[4:5], v[124:125]
	v_pk_mul_f32 v[6:7], v[6:7], v[126:127]
	v_cvt_pk_bf16_f32 v4, v4, v5
	v_cvt_pk_bf16_f32 v5, v6, v7
	v_pk_mul_f32 v[0:1], v[0:1], v[124:125]
	v_pk_mul_f32 v[2:3], v[2:3], v[126:127]
	global_store_dwordx2 v[38:39], v[4:5], off offset:1536
	v_cvt_pk_bf16_f32 v0, v0, v1
	v_cvt_pk_bf16_f32 v1, v2, v3
	v_lshl_add_u64 v[38:39], v[38:39], 0, s[40:41]
	global_store_dwordx2 v[46:47], v[0:1], off offset:1536
	s_cbranch_scc0 .LBB0_1064

; __device__ __forceinline__ void rms_row_f32(float* xrow, const float* g, int lane) {
;     f32x4* xr = (f32x4*)xrow + lane; const f32x4* gr = (const f32x4*)g + lane;
;     f32x4 v[4]; float s = 0.f;
; #pragma unroll
;     for (int j = 0; j < 4; ++j) { v[j] = xr[64 * j]; s += (v[j].x * v[j].x + v[j].y * v[j].y) + (v[j].z * v[j].z + v[j].w * v[j].w); }
;     const float r = rsqrtf(wave_sum(s) * (1.f / 1024.f) + 1e-6f);
; #pragma unroll
;     for (int j = 0; j < 4; ++j) { const f32x4 gg = gr[64 * j]; xr[64 * j] = v[j] * r * gg; }
; }
; __global__ void __launch_bounds__(NTHR, 2) fwd_megakernel(Params prm) {
;     ...
;     for (int row = bid * 8 + C.wave; row < M_TOK; row += G * 8) rms_row_f32(C.out + (size_t)row * 1024, C.P->in[30], C.lane);
.LBB0_1261:
	v_readlane_b32 s1, v253, 32
	v_readfirstlane_b32 s0, v224
	s_ashr_i32 s0, s0, 6
	s_add_i32 s0, s0, s1
	s_mov_b64 s[2:3], 0
	s_cmpk_gt_i32 s0, 0x7fff
	v_readlane_b32 s6, v254, 20
	v_readlane_b32 s7, v254, 21
	s_cbranch_scc1 .LBB0_1264
	v_readlane_b32 s8, v251, 52
	v_and_b32_e32 v4, 64, v221
	v_readlane_b32 s12, v251, 56
	v_readlane_b32 s13, v251, 57
	v_readlane_b32 s14, v251, 58
	v_readlane_b32 s15, v251, 59
	v_readlane_b32 s20, v252, 0
	v_readlane_b32 s21, v252, 1
	v_add_u32_e32 v9, 64, v4
	v_xor_b32_e32 v4, 1, v221
	v_readlane_b32 s22, v252, 2
	v_readlane_b32 s23, v252, 3
	s_mov_b64 s[12:13], s[20:21]
	v_cmp_lt_i32_e32 vcc, v4, v9
	v_xor_b32_e32 v5, 2, v221
	s_ashr_i32 s1, s0, 31
	s_mov_b64 s[14:15], s[22:23]
	v_cndmask_b32_e32 v4, v221, v4, vcc
	v_cmp_lt_i32_e32 vcc, v5, v9
	v_xor_b32_e32 v6, 4, v221
	s_lshl_b64 s[4:5], s[0:1], 12
	s_lshl_b64 s[2:3], s[2:3], 2
	v_cndmask_b32_e32 v5, v221, v5, vcc
	v_cmp_lt_i32_e32 vcc, v6, v9
	v_xor_b32_e32 v7, 8, v221
	s_add_u32 s1, s14, s2
	v_cndmask_b32_e32 v6, v221, v6, vcc
	v_cmp_lt_i32_e32 vcc, v7, v9
	v_xor_b32_e32 v8, 16, v221
	s_addc_u32 s3, s15, s3
	v_and_b32_e32 v0, 63, v224
	v_cndmask_b32_e32 v7, v221, v7, vcc
	v_cmp_lt_i32_e32 vcc, v8, v9
	v_xor_b32_e32 v10, 32, v221
	s_add_u32 s2, s1, s4
	v_lshlrev_b32_e32 v2, 4, v0
	v_mov_b32_e32 v3, 0
	v_cndmask_b32_e32 v8, v221, v8, vcc
	v_cmp_lt_i32_e32 vcc, v10, v9
	s_addc_u32 s3, s3, s5
	v_lshl_add_u64 v[0:1], s[12:13], 0, v[2:3]
	v_cndmask_b32_e32 v9, v221, v10, vcc
	v_lshl_add_u64 v[2:3], s[2:3], 0, v[2:3]
	s_mov_b64 s[2:3], 0xc00
	v_lshlrev_b32_e32 v4, 2, v4
	v_lshlrev_b32_e32 v5, 2, v5
	v_lshlrev_b32_e32 v6, 2, v6
	v_lshlrev_b32_e32 v7, 2, v7
	v_lshlrev_b32_e32 v8, 2, v8
	v_lshlrev_b32_e32 v9, 2, v9
	v_lshl_add_u64 v[2:3], v[2:3], 0, s[2:3]
	v_mov_b32_e32 v10, 0x358637bd
	s_mov_b32 s1, 0x800000
	v_readlane_b32 s9, v251, 53
	v_readlane_b32 s10, v251, 54
	v_readlane_b32 s11, v251, 55
	v_readlane_b32 s16, v251, 60
	v_readlane_b32 s17, v251, 61
	v_readlane_b32 s18, v251, 62
	v_readlane_b32 s19, v251, 63
	global_load_dwordx4 v[112:115], v[0:1], off offset:1024
	global_load_dwordx4 v[116:119], v[0:1], off offset:2048
	global_load_dwordx4 v[120:123], v[0:1], off offset:3072
	s_waitcnt vmcnt(0)
.LBB0_1263:
	global_load_dwordx4 v[12:15], v[2:3], off offset:-3072
	global_load_dwordx4 v[16:19], v[2:3], off offset:-2048
	global_load_dwordx4 v[20:23], v[2:3], off
	global_load_dwordx4 v[24:27], v[2:3], off offset:-1024
	global_load_dwordx4 v[28:31], v[0:1], off
	s_add_i32 s0, s0, s6
	s_cmpk_gt_i32 s0, 0x7fff
	s_waitcnt vmcnt(4)
	v_pk_mul_f32 v[32:33], v[14:15], v[14:15]
	v_pk_mul_f32 v[34:35], v[12:13], v[12:13]
	s_waitcnt vmcnt(3)
	v_pk_mul_f32 v[36:37], v[18:19], v[18:19]
	v_pk_mul_f32 v[38:39], v[16:17], v[16:17]
	v_pk_mov_b32 v[44:45], v[34:35], v[32:33] op_sel:[1,0]
	v_mov_b32_e32 v35, v33
	v_pk_mov_b32 v[32:33], v[38:39], v[36:37] op_sel:[1,0]
	v_mov_b32_e32 v39, v37
	s_waitcnt vmcnt(2)
	v_mul_f32_e32 v43, v21, v21
	s_waitcnt vmcnt(1)
	v_mul_f32_e32 v40, v25, v25
	v_mul_f32_e32 v42, v27, v27
	v_pk_add_f32 v[34:35], v[44:45], v[34:35]
	v_pk_add_f32 v[32:33], v[32:33], v[38:39]
	v_mul_f32_e32 v11, v20, v20
	v_mul_f32_e32 v46, v22, v22
	v_mul_f32_e32 v47, v23, v23
	v_pk_fma_f32 v[36:37], v[24:25], v[24:25], v[40:41] op_sel_hi:[1,1,0]
	v_pk_fma_f32 v[40:41], v[26:27], v[26:27], v[42:43] op_sel_hi:[1,1,0]
	v_pk_add_f32 v[34:35], v[34:35], v[34:35] op_sel:[0,1] op_sel_hi:[1,0]
	v_pk_add_f32 v[32:33], v[32:33], v[32:33] op_sel:[0,1] op_sel_hi:[1,0]
	v_mov_b32_e32 v37, v46
	v_mov_b32_e32 v41, v47
	v_mov_b32_e32 v35, v11
	v_mov_b32_e32 v33, v43
	v_pk_add_f32 v[36:37], v[36:37], v[40:41]
	v_pk_add_f32 v[32:33], v[34:35], v[32:33]
	s_nop 0
	v_pk_add_f32 v[32:33], v[32:33], v[36:37]
	s_nop 0
	v_add_f32_e32 v11, v32, v33
	ds_bpermute_b32 v32, v4, v11
	s_waitcnt lgkmcnt(0)
	v_add_f32_e32 v11, v11, v32
	ds_bpermute_b32 v32, v5, v11
	s_waitcnt lgkmcnt(0)
	v_add_f32_e32 v11, v11, v32
	ds_bpermute_b32 v32, v6, v11
	s_waitcnt lgkmcnt(0)
	v_add_f32_e32 v11, v11, v32
	ds_bpermute_b32 v32, v7, v11
	s_waitcnt lgkmcnt(0)
	v_add_f32_e32 v11, v11, v32
	ds_bpermute_b32 v32, v8, v11
	s_waitcnt lgkmcnt(0)
	v_add_f32_e32 v11, v11, v32
	ds_bpermute_b32 v32, v9, v11
	s_waitcnt lgkmcnt(0)
	v_add_f32_e32 v11, v11, v32
	v_fmamk_f32 v11, v11, 0x3a800000, v10
	v_mul_f32_e32 v32, 0x4b800000, v11
	v_cmp_gt_f32_e32 vcc, s1, v11
	s_nop 1
	v_cndmask_b32_e32 v11, v11, v32, vcc
	v_rsq_f32_e32 v11, v11
	s_nop 0
	v_mul_f32_e32 v32, 0x45800000, v11
	v_cndmask_b32_e32 v32, v11, v32, vcc
	v_pk_mul_f32 v[12:13], v[12:13], v[32:33] op_sel_hi:[1,0]
	v_pk_mul_f32 v[14:15], v[14:15], v[32:33] op_sel_hi:[1,0]
	s_waitcnt vmcnt(0)
	v_pk_mul_f32 v[12:13], v[28:29], v[12:13]
	v_pk_mul_f32 v[14:15], v[30:31], v[14:15]
	global_store_dwordx4 v[2:3], v[12:15], off offset:-3072
	v_pk_mul_f32 v[18:19], v[18:19], v[32:33] op_sel_hi:[1,0]
	v_pk_mul_f32 v[16:17], v[16:17], v[32:33] op_sel_hi:[1,0]
	v_pk_mul_f32 v[14:15], v[114:115], v[18:19]
	v_pk_mul_f32 v[12:13], v[112:113], v[16:17]
	global_store_dwordx4 v[2:3], v[12:15], off offset:-2048
	v_pk_mul_f32 v[16:17], v[26:27], v[32:33] op_sel_hi:[1,0]
	v_pk_mul_f32 v[18:19], v[24:25], v[32:33] op_sel_hi:[1,0]
	v_pk_mul_f32 v[14:15], v[118:119], v[16:17]
	v_pk_mul_f32 v[12:13], v[116:117], v[18:19]
	global_store_dwordx4 v[2:3], v[12:15], off offset:-1024
	v_pk_mul_f32 v[16:17], v[22:23], v[32:33] op_sel_hi:[1,0]
	v_pk_mul_f32 v[18:19], v[20:21], v[32:33] op_sel_hi:[1,0]
	v_pk_mul_f32 v[14:15], v[122:123], v[16:17]
	v_pk_mul_f32 v[12:13], v[120:121], v[18:19]
	global_store_dwordx4 v[2:3], v[12:15], off
	v_lshl_add_u64 v[2:3], v[2:3], 0, s[52:53]
	s_cbranch_scc0 .LBB0_1263
